# P3: LoRA-up and RG-gate GEMMs run one K-loop pass per unit on the K half that holds their non-zero weight block (structural zeros of WLORA / WRG skipped)
# speedup vs baseline: 1.0122x; 1.0122x over previous
.LBB0_736:
	s_lshl_b32 s5, s33, 5
	s_lshr_b32 s4, s87, 8
	s_and_b32 s22, s5, 0x60
	s_lshl_b32 s70, s33, 10
	s_lshl_b32 s27, s4, 6
	s_lshl_b32 s26, s4, 13
	s_lshr_b32 s23, s22, 3
	s_cmp_eq_u32 s4, 1
	s_cselect_b64 s[4:5], -1, 0
	s_cmpk_lt_u32 s87, 0x100
	v_cndmask_b32_e64 v0, 0, 1, s[4:5]
	s_cselect_b64 s[12:13], -1, 0
	s_ashr_i32 s71, s92, 31
	s_andn2_b64 vcc, exec, s[0:1]
	v_cmp_ne_u32_e64 s[0:1], 1, v0
	s_cbranch_vccnz .LBB0_792
	v_lshl_add_u32 v0, v8, 4, s70
	v_ashrrev_i32_e32 v1, 31, v0
	v_lshrrev_b32_e32 v1, 22, v1
	v_add_u32_e32 v1, v0, v1
	v_ashrrev_i32_e32 v1, 10, v1
	v_mul_i32_i24_e32 v2, 0x400, v1
	v_sub_u32_e32 v2, v0, v2
	v_lshrrev_b32_e32 v3, 4, v2
	v_bitop3_b32 v2, v3, v2, 32 bitop3:0x6c
	v_ashrrev_i32_e32 v4, 31, v2
	v_lshrrev_b32_e32 v4, 26, v4
	v_lshlrev_b32_e32 v3, 3, v1
	v_add_u32_e32 v4, v2, v4
	v_and_b32_e32 v3, -16, v3
	v_ashrrev_i32_e32 v5, 6, v4
	v_and_b32_e32 v4, 0xc0, v4
	v_add_u32_e32 v3, v5, v3
	v_sub_u32_e32 v2, v2, v4
	v_mov_b32_e32 v4, 1
	v_lshlrev_b32_e32 v1, 5, v1
	v_ashrrev_i16_sdwa v2, v4, sext(v2) dst_sel:DWORD dst_unused:UNUSED_PAD src0_sel:DWORD src1_sel:BYTE_0
	v_lshlrev_b32_e32 v6, 1, v3
	v_lshrrev_b32_e32 v7, 2, v3
	v_and_b32_e32 v5, 3, v5
	s_mov_b32 s4, 0x7fffe0
	v_and_b32_e32 v1, 32, v1
	v_bfe_i32 v2, v2, 0, 16
	v_and_b32_e32 v6, 24, v6
	v_and_b32_e32 v7, 4, v7
	v_and_or_b32 v5, v3, s4, v5
	v_or3_b32 v5, v5, v7, v6
	v_add_lshl_u32 v1, v1, v2, 1
	v_add_u32_e32 v0, 0x2000, v0
	v_lshl_add_u32 v144, v3, 9, v1
	v_lshl_add_u32 v146, v5, 9, v1
	v_ashrrev_i32_e32 v1, 31, v0
	v_lshrrev_b32_e32 v1, 22, v1
	v_add_u32_e32 v1, v0, v1
	v_ashrrev_i32_e32 v1, 10, v1
	v_mul_i32_i24_e32 v2, 0x400, v1
	v_sub_u32_e32 v0, v0, v2
	v_lshrrev_b32_e32 v2, 4, v0
	v_bitop3_b32 v0, v2, v0, 32 bitop3:0x6c
	v_ashrrev_i32_e32 v3, 31, v0
	s_add_u32 s74, s96, 0x25800000
	v_lshrrev_b32_e32 v3, 26, v3
	v_writelane_b32 v255, s9, 44
	s_addc_u32 s75, s97, 0
	v_lshlrev_b32_e32 v2, 3, v1
	v_add_u32_e32 v3, v0, v3
	v_writelane_b32 v255, s10, 45
	s_add_u32 s78, s96, 0x2700000
	v_and_b32_e32 v2, -16, v2
	v_ashrrev_i32_e32 v5, 6, v3
	v_writelane_b32 v255, s11, 46
	s_addc_u32 s85, s97, 0
	v_add_u32_e32 v2, v5, v2
	v_and_b32_e32 v3, 0xffc0, v3
	v_and_b32_e32 v5, 3, v5
	s_ashr_i32 s31, s30, 31
	s_ashr_i32 s7, s6, 31
	v_writelane_b32 v255, s8, 47
	v_sub_u32_e32 v0, v0, v3
	v_and_or_b32 v5, v2, s4, v5
	s_lshl_b64 s[4:5], s[30:31], 17
	s_lshl_b64 s[8:9], s[6:7], 17
	v_lshrrev_b16_e32 v3, 7, v0
	s_add_u32 s8, s78, s8
	v_and_b32_e32 v3, 1, v3
	s_addc_u32 s9, s85, s9
	s_cmp_gt_i32 s6, 3
	s_cselect_b32 s101, 0x100, 0
	s_add_u32 s8, s8, s101
	s_addc_u32 s9, s9, 0
	s_add_i32 s31, s70, 0
	v_add_u16_e32 v0, v0, v3
	s_add_i32 m0, s31, 0x10000
	v_lshlrev_b32_e32 v1, 5, v1
	v_ashrrev_i16_sdwa v0, v4, sext(v0) dst_sel:DWORD dst_unused:UNUSED_PAD src0_sel:DWORD src1_sel:BYTE_0
	v_lshlrev_b32_e32 v3, 1, v2
	v_lshrrev_b32_e32 v4, 2, v2
	global_load_lds_dwordx4 v146, s[8:9]
	s_add_i32 m0, s31, 0x12000
	v_and_b32_e32 v1, 32, v1
	v_bfe_i32 v0, v0, 0, 16
	v_and_b32_e32 v3, 24, v3
	v_and_b32_e32 v4, 4, v4
	s_add_u32 s34, s74, s4
	v_or3_b32 v3, v5, v4, v3
	v_add_lshl_u32 v0, v1, v0, 1
	s_addc_u32 s35, s75, s5
	s_add_u32 s34, s34, s101
	s_addc_u32 s35, s35, 0
	v_lshl_add_u32 v150, v3, 9, v0
	s_add_u32 s4, s8, 0x10000
	global_load_lds_dwordx4 v150, s[8:9]
	s_addc_u32 s5, s9, 0
	s_add_i32 m0, s31, 0x14000
	s_add_i32 s90, s31, 0x2000
	global_load_lds_dwordx4 v146, s[4:5]
	s_add_i32 m0, s31, 0x16000
	v_lshl_add_u32 v148, v2, 9, v0
	global_load_lds_dwordx4 v150, s[4:5]
	s_mov_b32 m0, s31
	s_add_u32 s4, s34, 0x10000
	global_load_lds_dwordx4 v144, s[34:35]
	s_mov_b32 m0, s90
	s_addc_u32 s5, s35, 0
	s_add_i32 s91, s31, 0x4000
	global_load_lds_dwordx4 v148, s[34:35]
	s_mov_b32 m0, s91
	s_add_i32 s11, s31, 0x6000
	global_load_lds_dwordx4 v144, s[4:5]
	s_mov_b32 m0, s11
	v_writelane_b32 v255, s64, 38
	global_load_lds_dwordx4 v148, s[4:5]
	v_mov_b32_e32 v147, 0
	v_writelane_b32 v255, s65, 39
	v_mov_b32_e32 v151, v147
	v_mov_b32_e32 v145, v147
	v_mov_b32_e32 v149, v147
	v_writelane_b32 v255, s86, 36
	v_lshl_add_u64 v[6:7], s[8:9], 0, v[146:147]
	s_mov_b32 s79, 0
	v_lshl_add_u64 v[4:5], s[8:9], 0, v[150:151]
	v_lshl_add_u64 v[2:3], s[34:35], 0, v[144:145]
	s_and_b64 vcc, exec, s[0:1]
	v_lshl_add_u64 v[0:1], s[34:35], 0, v[148:149]
	s_cbranch_vccnz .LBB0_739
	s_barrier

.LBB0_744:
	s_ashr_i32 s23, s22, 31
	s_lshl_b64 s[26:27], s[22:23], 17
	s_add_u32 s26, s74, s26
	s_addc_u32 s27, s75, s27
	s_cmp_gt_i32 s20, 3
	s_cselect_b32 s101, 0x100, 0
	s_add_u32 s26, s26, s101
	s_addc_u32 s27, s27, 0
	s_and_b64 s[28:29], s[4:5], exec
	s_cselect_b32 s7, s27, s35
	s_cselect_b32 s23, s26, s34
	s_ashr_i32 s21, s20, 31
	s_lshl_b64 s[28:29], s[20:21], 17
	s_add_u32 s28, s78, s28
	s_addc_u32 s29, s85, s29
	s_add_u32 s28, s28, s101
	s_addc_u32 s29, s29, 0
	s_and_b64 s[38:39], s[4:5], exec
	v_mov_b32_e32 v0, 0
	s_cselect_b32 s21, s29, s9
	s_cselect_b32 s73, s28, s8
	s_mov_b32 s42, 0
	s_mov_b64 s[38:39], 0
	s_mov_b64 s[40:41], -1
	v_mov_b32_e32 v1, v0
	v_mov_b32_e32 v2, v0
	v_mov_b32_e32 v3, v0
	v_mov_b32_e32 v4, v0
	v_mov_b32_e32 v5, v0
	v_mov_b32_e32 v6, v0
	v_mov_b32_e32 v7, v0
	v_mov_b32_e32 v16, v0
	v_mov_b32_e32 v17, v0
	v_mov_b32_e32 v18, v0
	v_mov_b32_e32 v19, v0
	v_mov_b32_e32 v20, v0
	v_mov_b32_e32 v21, v0
	v_mov_b32_e32 v22, v0
	v_mov_b32_e32 v23, v0
	v_mov_b32_e32 v32, v0
	v_mov_b32_e32 v33, v0
	v_mov_b32_e32 v34, v0
	v_mov_b32_e32 v35, v0
	v_mov_b32_e32 v36, v0
	v_mov_b32_e32 v37, v0
	v_mov_b32_e32 v38, v0
	v_mov_b32_e32 v39, v0
	v_mov_b32_e32 v48, v0
	v_mov_b32_e32 v49, v0
	v_mov_b32_e32 v50, v0
	v_mov_b32_e32 v51, v0
	v_mov_b32_e32 v52, v0
	v_mov_b32_e32 v53, v0
	v_mov_b32_e32 v54, v0
	v_mov_b32_e32 v55, v0
	v_mov_b32_e32 v8, v0
	v_mov_b32_e32 v9, v0
	v_mov_b32_e32 v10, v0
	v_mov_b32_e32 v11, v0
	s_waitcnt vmcnt(0)
	v_mov_b32_e32 v12, v0
	v_mov_b32_e32 v13, v0
	v_mov_b32_e32 v14, v0
	v_mov_b32_e32 v15, v0
	v_mov_b32_e32 v24, v0
	v_mov_b32_e32 v25, v0
	v_mov_b32_e32 v26, v0
	v_mov_b32_e32 v27, v0
	v_mov_b32_e32 v28, v0
	v_mov_b32_e32 v29, v0
	v_mov_b32_e32 v30, v0
	v_mov_b32_e32 v31, v0
	v_mov_b32_e32 v40, v0
	v_mov_b32_e32 v41, v0
	v_mov_b32_e32 v42, v0
	v_mov_b32_e32 v43, v0
	v_mov_b32_e32 v44, v0
	v_mov_b32_e32 v45, v0
	v_mov_b32_e32 v46, v0
	v_mov_b32_e32 v47, v0
	v_mov_b32_e32 v56, v0
	v_mov_b32_e32 v57, v0
	v_mov_b32_e32 v58, v0
	v_mov_b32_e32 v59, v0
	v_mov_b32_e32 v60, v0
	v_mov_b32_e32 v61, v0
	v_mov_b32_e32 v62, v0
	v_mov_b32_e32 v63, v0
	v_mov_b32_e32 v72, v0
	v_mov_b32_e32 v73, v0
	v_mov_b32_e32 v74, v0
	v_mov_b32_e32 v75, v0
	v_mov_b32_e32 v80, v0
	v_mov_b32_e32 v81, v0
	v_mov_b32_e32 v82, v0
	v_mov_b32_e32 v83, v0
	v_mov_b32_e32 v96, v0
	v_mov_b32_e32 v97, v0
	v_mov_b32_e32 v98, v0
	v_mov_b32_e32 v99, v0
	v_mov_b32_e32 v100, v0
	v_mov_b32_e32 v101, v0
	v_mov_b32_e32 v102, v0
	v_mov_b32_e32 v103, v0
	v_mov_b32_e32 v112, v0
	v_mov_b32_e32 v113, v0
	v_mov_b32_e32 v114, v0
	v_mov_b32_e32 v115, v0
	v_mov_b32_e32 v116, v0
	v_mov_b32_e32 v117, v0
	v_mov_b32_e32 v118, v0
	v_mov_b32_e32 v119, v0
	v_mov_b32_e32 v128, v0
	v_mov_b32_e32 v129, v0
	v_mov_b32_e32 v130, v0
	v_mov_b32_e32 v131, v0
	v_mov_b32_e32 v132, v0
	v_mov_b32_e32 v133, v0
	v_mov_b32_e32 v134, v0
	v_mov_b32_e32 v135, v0
	v_mov_b32_e32 v88, v0
	v_mov_b32_e32 v89, v0
	v_mov_b32_e32 v90, v0
	v_mov_b32_e32 v91, v0
	v_mov_b32_e32 v92, v0
	v_mov_b32_e32 v93, v0
	v_mov_b32_e32 v94, v0
	v_mov_b32_e32 v95, v0
	v_mov_b32_e32 v104, v0
	v_mov_b32_e32 v105, v0
	v_mov_b32_e32 v106, v0
	v_mov_b32_e32 v107, v0
	v_mov_b32_e32 v108, v0
	v_mov_b32_e32 v109, v0
	v_mov_b32_e32 v110, v0
	v_mov_b32_e32 v111, v0
	v_mov_b32_e32 v120, v0
	v_mov_b32_e32 v121, v0
	v_mov_b32_e32 v122, v0
	v_mov_b32_e32 v123, v0
	v_mov_b32_e32 v124, v0
	v_mov_b32_e32 v125, v0
	v_mov_b32_e32 v126, v0
	v_mov_b32_e32 v127, v0
	v_mov_b32_e32 v136, v0
	v_mov_b32_e32 v137, v0
	v_mov_b32_e32 v138, v0
	v_mov_b32_e32 v139, v0
	v_mov_b32_e32 v140, v0
	v_mov_b32_e32 v141, v0
	v_mov_b32_e32 v142, v0
	v_mov_b32_e32 v143, v0

.LBB0_792:
	s_cmpk_gt_i32 s2, 0x3ff
	v_mbcnt_lo_u32_b32 v8, -1, 0
	v_mbcnt_hi_u32_b32 v8, -1, v8
	s_cbranch_scc1 .LBB0_814
	v_lshl_add_u32 v0, v8, 4, s70
	v_add_u32_e32 v1, 0x2000, v0
	v_ashrrev_i32_e32 v2, 31, v1
	v_lshrrev_b32_e32 v2, 22, v2
	v_add_u32_e32 v2, v1, v2
	v_ashrrev_i32_e32 v2, 10, v2
	v_mul_i32_i24_e32 v3, 0x400, v2
	v_sub_u32_e32 v1, v1, v3
	v_lshrrev_b32_e32 v3, 4, v1
	v_bitop3_b32 v1, v3, v1, 32 bitop3:0x6c
	v_ashrrev_i32_e32 v3, 31, v1
	v_lshrrev_b32_e32 v3, 26, v3
	v_add_u32_e32 v3, v1, v3
	v_ashrrev_i32_e32 v4, 6, v3
	v_and_b32_e32 v3, 0xffc0, v3
	v_sub_u32_e32 v1, v1, v3
	v_lshlrev_b32_e32 v5, 3, v2
	v_lshrrev_b16_e32 v3, 7, v1
	v_and_b32_e32 v5, -16, v5
	v_and_b32_e32 v3, 1, v3
	v_add_u32_e32 v5, v4, v5
	v_add_u16_e32 v1, v1, v3
	v_mov_b32_e32 v3, 1
	v_and_b32_e32 v4, 3, v4
	s_mov_b32 s4, 0x7fffe0
	v_lshrrev_b32_e32 v6, 2, v5
	v_lshlrev_b32_e32 v7, 1, v5
	v_lshlrev_b32_e32 v2, 5, v2
	v_ashrrev_i16_sdwa v1, v3, sext(v1) dst_sel:DWORD dst_unused:UNUSED_PAD src0_sel:DWORD src1_sel:BYTE_0
	v_and_or_b32 v4, v5, s4, v4
	v_and_b32_e32 v6, 4, v6
	v_and_b32_e32 v7, 24, v7
	v_and_b32_e32 v2, 32, v2
	v_bfe_i32 v1, v1, 0, 16
	v_or3_b32 v4, v4, v6, v7
	v_add_lshl_u32 v1, v2, v1, 1
	v_lshl_add_u32 v152, v4, 9, v1
	v_lshl_add_u32 v154, v5, 10, v1
	v_ashrrev_i32_e32 v1, 31, v0
	v_lshrrev_b32_e32 v1, 22, v1
	v_add_u32_e32 v1, v0, v1
	v_ashrrev_i32_e32 v1, 10, v1
	v_mul_i32_i24_e32 v2, 0x400, v1
	v_sub_u32_e32 v0, v0, v2
	v_lshrrev_b32_e32 v2, 4, v0
	v_bitop3_b32 v0, v2, v0, 32 bitop3:0x6c
	v_ashrrev_i32_e32 v2, 31, v0
	s_add_u32 s14, s96, 0x27800000
	v_lshrrev_b32_e32 v2, 26, v2
	s_addc_u32 s15, s97, 0
	v_add_u32_e32 v2, v0, v2
	v_lshlrev_b32_e32 v5, 3, v1
	s_add_u32 s56, s96, 0x2800000
	v_ashrrev_i32_e32 v4, 6, v2
	v_and_b32_e32 v5, -16, v5
	s_addc_u32 s57, s97, 0
	s_lshl_b32 s6, s9, 7
	v_add_u32_e32 v5, v4, v5
	v_and_b32_e32 v4, 3, v4
	s_mul_i32 s7, s9, 0x81
	v_and_or_b32 v4, v5, s4, v4
	s_and_b64 s[4:5], s[10:11], exec
	s_cselect_b32 s4, s7, s6
	s_add_i32 s4, s4, s8
	s_ashr_i32 s5, s4, 31
	s_lshr_b32 s5, s5, 27
	s_add_i32 s5, s4, s5
	s_ashr_i32 s6, s5, 5
	s_andn2_b32 s5, s5, 31
	s_sub_i32 s5, s4, s5
	s_bfe_i32 s4, s5, 0x80000
	s_bfe_u32 s4, s4, 0x3000c
	s_add_i32 s8, s5, s4
	s_bfe_i32 s4, s8, 0x80000
	s_and_b32 s8, s8, 0xf8
	s_sub_i32 s5, s5, s8
	s_lshl_b32 s7, s6, 3
	s_sext_i32_i16 s4, s4
	s_sext_i32_i8 s5, s5
	v_and_b32_e32 v2, 0xc0, v2
	s_lshr_b32 s6, s4, 3
	s_add_i32 s8, s7, s5
	s_ashr_i32 s16, s4, 4
	v_sub_u32_e32 v0, v0, v2
	s_ashr_i32 s9, s8, 31
	s_bfe_i64 s[6:7], s[6:7], 0x100000
	s_and_b32 s101, s6, 1
	s_lshl_b32 s101, s101, 8
	s_ashr_i32 s17, s16, 31
	v_lshrrev_b32_e32 v6, 2, v5
	v_lshlrev_b32_e32 v7, 1, v5
	v_lshlrev_b32_e32 v1, 5, v1
	v_ashrrev_i16_sdwa v0, v3, sext(v0) dst_sel:DWORD dst_unused:UNUSED_PAD src0_sel:DWORD src1_sel:BYTE_0
	s_lshl_b64 s[10:11], s[8:9], 18
	s_lshl_b64 s[16:17], s[16:17], 9
	s_lshl_b64 s[6:7], s[6:7], 17
	v_and_b32_e32 v6, 4, v6
	v_and_b32_e32 v7, 24, v7
	v_and_b32_e32 v1, 32, v1
	v_bfe_i32 v0, v0, 0, 16
	s_add_u32 s34, s56, s6
	v_or3_b32 v4, v4, v6, v7
	v_add_lshl_u32 v0, v1, v0, 1
	s_addc_u32 s35, s57, s7
	s_add_u32 s34, s34, s101
	s_addc_u32 s35, s35, 0
	s_add_i32 s68, s70, 0
	v_lshl_add_u32 v156, v4, 9, v0
	s_add_i32 m0, s68, 0x10000
	v_lshl_add_u32 v158, v5, 10, v0
	global_load_lds_dwordx4 v156, s[34:35]
	s_add_i32 m0, s68, 0x12000
	s_add_u32 s5, s14, s10
	s_addc_u32 s9, s15, s11
	s_add_u32 s6, s34, 0x10000
	global_load_lds_dwordx4 v152, s[34:35]
	s_addc_u32 s7, s35, 0
	s_add_i32 m0, s68, 0x14000
	v_mov_b32_e32 v157, 0
	global_load_lds_dwordx4 v156, s[6:7]
	s_add_i32 m0, s68, 0x16000
	s_add_u32 s38, s5, s16
	s_addc_u32 s39, s9, s17
	s_add_u32 s38, s38, s101
	s_addc_u32 s39, s39, 0
	s_add_i32 s69, s68, 0x2000
	global_load_lds_dwordx4 v152, s[6:7]
	s_mov_b32 m0, s68
	s_add_u32 s6, s38, 0x20000
	global_load_lds_dwordx4 v158, s[38:39]
	s_mov_b32 m0, s69
	s_addc_u32 s7, s39, 0
	s_add_i32 s72, s68, 0x4000
	global_load_lds_dwordx4 v154, s[38:39]
	s_mov_b32 m0, s72
	s_add_i32 s73, s68, 0x6000
	global_load_lds_dwordx4 v158, s[6:7]
	s_mov_b32 m0, s73
	v_mov_b32_e32 v153, v157
	global_load_lds_dwordx4 v154, s[6:7]
	v_mov_b32_e32 v159, v157
	v_mov_b32_e32 v155, v157
	s_mov_b32 s63, s86
	v_lshl_add_u64 v[6:7], s[34:35], 0, v[156:157]
	s_mov_b32 s74, 0
	v_lshl_add_u64 v[4:5], s[34:35], 0, v[152:153]
	v_lshl_add_u64 v[2:3], s[38:39], 0, v[158:159]
	s_and_b64 vcc, exec, s[0:1]
	v_lshl_add_u64 v[0:1], s[38:39], 0, v[154:155]
	s_cbranch_vccnz .LBB0_795
	s_barrier

.LBB0_804:
	s_nop 0
	v_cndmask_b32_e64 v0, 0, 1, s[6:7]
	v_cmp_ne_u32_e64 s[4:5], 1, v0
	s_andn2_b64 vcc, exec, s[6:7]
	s_mov_b64 s[28:29], s[38:39]
	s_cbranch_vccnz .LBB0_806
	s_ashr_i32 s27, s26, 31
	s_lshl_b64 s[28:29], s[26:27], 18
	s_add_u32 s23, s14, s28
	s_addc_u32 s27, s15, s29
	s_ashr_i32 s28, s22, 1
	s_ashr_i32 s29, s28, 31
	s_lshl_b64 s[28:29], s[28:29], 9
	s_add_u32 s28, s23, s28
	s_addc_u32 s29, s27, s29
	s_and_b32 s101, s22, 1
	s_lshl_b32 s101, s101, 8
	s_add_u32 s28, s28, s101
	s_addc_u32 s29, s29, 0
.LBB0_806:
	s_ashr_i32 s23, s22, 31
	s_lshl_b64 s[30:31], s[22:23], 17
	s_add_u32 s30, s56, s30
	s_addc_u32 s31, s57, s31
	s_and_b32 s101, s22, 1
	s_lshl_b32 s101, s101, 8
	s_add_u32 s30, s30, s101
	s_addc_u32 s31, s31, 0
	s_and_b64 s[6:7], s[6:7], exec
	v_mov_b32_e32 v0, 0
	s_cselect_b32 s23, s31, s35
	s_cselect_b32 s27, s30, s34
	s_mov_b32 s42, 0
	s_mov_b64 s[6:7], 0
	s_mov_b64 s[40:41], -1
	v_mov_b32_e32 v1, v0
	v_mov_b32_e32 v2, v0
	v_mov_b32_e32 v3, v0
	v_mov_b32_e32 v8, v0
	v_mov_b32_e32 v9, v0
	v_mov_b32_e32 v10, v0
	v_mov_b32_e32 v11, v0
	v_mov_b32_e32 v16, v0
	v_mov_b32_e32 v17, v0
	v_mov_b32_e32 v18, v0
	v_mov_b32_e32 v19, v0
	v_mov_b32_e32 v24, v0
	v_mov_b32_e32 v25, v0
	v_mov_b32_e32 v26, v0
	v_mov_b32_e32 v27, v0
	v_mov_b32_e32 v32, v0
	v_mov_b32_e32 v33, v0
	v_mov_b32_e32 v34, v0
	v_mov_b32_e32 v35, v0
	v_mov_b32_e32 v48, v0
	v_mov_b32_e32 v49, v0
	v_mov_b32_e32 v50, v0
	v_mov_b32_e32 v51, v0
	v_mov_b32_e32 v64, v0
	v_mov_b32_e32 v65, v0
	v_mov_b32_e32 v66, v0
	v_mov_b32_e32 v67, v0
	v_mov_b32_e32 v72, v0
	v_mov_b32_e32 v73, v0
	v_mov_b32_e32 v74, v0
	v_mov_b32_e32 v75, v0
	v_mov_b32_e32 v4, v0
	v_mov_b32_e32 v5, v0
	v_mov_b32_e32 v6, v0
	v_mov_b32_e32 v7, v0
	s_waitcnt vmcnt(0)
	v_mov_b32_e32 v12, v0
	v_mov_b32_e32 v13, v0
	v_mov_b32_e32 v14, v0
	v_mov_b32_e32 v15, v0
	v_mov_b32_e32 v20, v0
	v_mov_b32_e32 v21, v0
	v_mov_b32_e32 v22, v0
	v_mov_b32_e32 v23, v0
	v_mov_b32_e32 v28, v0
	v_mov_b32_e32 v29, v0
	v_mov_b32_e32 v30, v0
	v_mov_b32_e32 v31, v0
	v_mov_b32_e32 v36, v0
	v_mov_b32_e32 v37, v0
	v_mov_b32_e32 v38, v0
	v_mov_b32_e32 v39, v0
	v_mov_b32_e32 v52, v0
	v_mov_b32_e32 v53, v0
	v_mov_b32_e32 v54, v0
	v_mov_b32_e32 v55, v0
	v_mov_b32_e32 v68, v0
	v_mov_b32_e32 v69, v0
	v_mov_b32_e32 v70, v0
	v_mov_b32_e32 v71, v0
	v_mov_b32_e32 v76, v0
	v_mov_b32_e32 v77, v0
	v_mov_b32_e32 v78, v0
	v_mov_b32_e32 v79, v0
	v_mov_b32_e32 v80, v0
	v_mov_b32_e32 v81, v0
	v_mov_b32_e32 v82, v0
	v_mov_b32_e32 v83, v0
	v_mov_b32_e32 v88, v0
	v_mov_b32_e32 v89, v0
	v_mov_b32_e32 v90, v0
	v_mov_b32_e32 v91, v0
	v_mov_b32_e32 v96, v0
	v_mov_b32_e32 v97, v0
	v_mov_b32_e32 v98, v0
	v_mov_b32_e32 v99, v0
	v_mov_b32_e32 v104, v0
	v_mov_b32_e32 v105, v0
	v_mov_b32_e32 v106, v0
	v_mov_b32_e32 v107, v0
	v_mov_b32_e32 v112, v0
	v_mov_b32_e32 v113, v0
	v_mov_b32_e32 v114, v0
	v_mov_b32_e32 v115, v0
	v_mov_b32_e32 v120, v0
	v_mov_b32_e32 v121, v0
	v_mov_b32_e32 v122, v0
	v_mov_b32_e32 v123, v0
	v_mov_b32_e32 v128, v0
	v_mov_b32_e32 v129, v0
	v_mov_b32_e32 v130, v0
	v_mov_b32_e32 v131, v0
	v_mov_b32_e32 v136, v0
	v_mov_b32_e32 v137, v0
	v_mov_b32_e32 v138, v0
	v_mov_b32_e32 v139, v0
	v_mov_b32_e32 v84, v0
	v_mov_b32_e32 v85, v0
	v_mov_b32_e32 v86, v0
	v_mov_b32_e32 v87, v0
	v_mov_b32_e32 v92, v0
	v_mov_b32_e32 v93, v0
	v_mov_b32_e32 v94, v0
	v_mov_b32_e32 v95, v0
	v_mov_b32_e32 v100, v0
	v_mov_b32_e32 v101, v0
	v_mov_b32_e32 v102, v0
	v_mov_b32_e32 v103, v0
	v_mov_b32_e32 v108, v0
	v_mov_b32_e32 v109, v0
	v_mov_b32_e32 v110, v0
	v_mov_b32_e32 v111, v0
	v_mov_b32_e32 v116, v0
	v_mov_b32_e32 v117, v0
	v_mov_b32_e32 v118, v0
	v_mov_b32_e32 v119, v0
	v_mov_b32_e32 v124, v0
	v_mov_b32_e32 v125, v0
	v_mov_b32_e32 v126, v0
	v_mov_b32_e32 v127, v0
	v_mov_b32_e32 v132, v0
	v_mov_b32_e32 v133, v0
	v_mov_b32_e32 v134, v0
	v_mov_b32_e32 v135, v0
	v_mov_b32_e32 v140, v0
	v_mov_b32_e32 v141, v0
	v_mov_b32_e32 v142, v0
	v_mov_b32_e32 v143, v0
